# tail conversion split re-tuned for the faster HGRN scan: HGRN waves take 8 of 11 rounds
# baseline (speedup 1.0000x reference)
.LBB0_512:
	v_readlane_b32 s0, v251, 36
	v_readlane_b32 s50, v251, 47
	v_readlane_b32 s1, v251, 37
	v_readlane_b32 s51, v251, 48
	s_and_b64 s[0:1], s[50:51], s[0:1]
	v_readlane_b32 s84, v251, 42
	s_andn2_b64 vcc, exec, s[0:1]
	v_readlane_b32 s60, v251, 40
	v_readlane_b32 s62, v251, 38
	v_readlane_b32 s85, v251, 43
	v_readlane_b32 s61, v251, 41
	v_readlane_b32 s63, v251, 39
	s_cbranch_vccnz .LBB0_539
	s_movk_i32 s93, 0x2000
	s_mov_b32 s94, 0
	s_cmpk_lt_i32 s64, 0x80
	s_cbranch_scc1 .Ltail_hgrn
	s_movk_i32 s93, 0x2c00
	s_movk_i32 s94, 0x1c00
	s_branch .Ltail_conv

.LBB0_536:
	s_waitcnt vmcnt(0)
	s_cmpk_gt_i32 s60, 0x1fff
	s_barrier
	s_waitcnt vmcnt(0)
	s_barrier
	s_cbranch_scc1 .LBB0_539
